# attention item prologue: Q fragments, scale parameter and K/V tile 0 requested together with the lambda parameters (one global round trip instead of four)
# baseline (speedup 1.0000x reference)
; DI float bf2f(unsigned v) { return __uint_as_float(v << 16); }
; DI f32x16 zero16() { f32x16 z; for (int i = 0; i < 16; ++i) z[i] = 0.f; return z; }
; DI void attn_item(const P& p, int l, int item, char* smem) {
;     ...
;   {
;     float s1 = p.lq1[l * 64 + lane] * p.lk1[l * 64 + lane];
;     float s2 = p.lq2[l * 64 + lane] * p.lk2[l * 64 + lane];
; #pragma unroll
;     for (int m = 32; m >= 1; m >>= 1) { s1 += __shfl_xor(s1, m); s2 += __shfl_xor(s2, m); }
;     lam = __expf(s1) - __expf(s2) + lam_init;
;   }
;   const int tq = qb * 128 + qg * 32 + li;
;   bf16x8 qf[4];
;   float negm;
;   {
;     float q2 = 0.f;
; #pragma unroll
;     for (int ks = 0; ks < 4; ++ks) {
;       qf[ks] = *(const bf16x8*)(p.Qb + ((size_t)((bh * 2 + c) * SEQ + tq)) * 64 + 16 * ks + 8 * g);
; #pragma unroll
;       for (int j = 0; j < 8; ++j) { const float v = bf2f((unsigned)(u16)qf[ks][j]); q2 += v * v; }
;     }
;     q2 += __shfl_xor(q2, 32);
;     const float k2 = __uint_as_float(p.kmax[bh * 2 + c]);
;     negm = -(sqrtf(q2 * k2) * 1.01f + 1e-3f);
;   }
;   f32x16 O[4];
; #pragma unroll
;   for (int eb = 0; eb < 4; ++eb) O[eb] = zero16();
;   float ls = 0.f;
;   u32x4 kreg[2], vreg[2];
;   const u16* kbase = p.Kb + (size_t)(bh * 2) * SEQ * 64;
;   const u16* vbase = p.VT + (size_t)(bh * 128) * VTP;
; #pragma unroll
;   for (int i = 0; i < 2; ++i) kreg[i] = *(const u32x4*)(kbase + ((size_t)i * SEQ) * 64 + tid * 8);
; #pragma unroll
;   for (int i = 0; i < 2; ++i) {
;     const int cid = tid + NT * i;
;     const int e = cid >> 3, kc = cid & 7;
;     vreg[i] = *(const u32x4*)(vbase + (size_t)e * VTP + kc * 8);
;   }
.LBB0_465:
	v_mov_b32_e32 v161, v198
	v_readlane_b32 s6, v248, 26
	v_and_b32_e32 v141, 63, v161
	v_readlane_b32 s72, v248, 30
	v_or_b32_e32 v188, s6, v141
	v_lshlrev_b64 v[0:1], 2, v[188:189]
	v_lshl_add_u64 v[2:3], s[22:23], 0, v[0:1]
	global_load_dword v4, v[2:3], off
	v_lshl_add_u64 v[2:3], s[24:25], 0, v[0:1]
	v_readlane_b32 s73, v248, 31
	global_load_dword v5, v[2:3], off
	v_lshl_add_u64 v[2:3], s[26:27], 0, v[0:1]
	v_lshl_add_u64 v[0:1], s[72:73], 0, v[0:1]
	global_load_dword v2, v[2:3], off
	v_and_b32_e32 v3, 64, v215
	global_load_dword v0, v[0:1], off
	v_add_u32_e32 v3, 64, v3
	v_xor_b32_e32 v7, 32, v215
	v_cmp_lt_i32_e32 vcc, v7, v3
	v_bfe_u32 v162, v161, 6, 2
	s_lshl_b32 s6, s95, 4
	v_cndmask_b32_e32 v7, v215, v7, vcc
	v_lshlrev_b32_e32 v158, 2, v7
	v_ashrrev_i32_e32 v160, 8, v161
	v_and_b32_e32 v17, 31, v161
	s_and_b32 s12, s95, 7
	s_and_b32 s6, s6, 0xffffff80
	v_bfe_u32 v159, v161, 5, 1
	v_lshlrev_b32_e32 v188, 4, v159
	s_and_b32 s13, s64, 7
	s_lshl_b32 s11, s13, 21
	v_mov_b32_e32 v143, v189
	v_ashrrev_i32_e32 v24, 3, v161
	s_movk_i32 s14, 0x4080
	v_mul_lo_u32 v170, v24, s94
	v_mov_b32_e32 v167, 0
	s_mov_b32 s10, 0
	v_mul_u32_u24_e32 v174, 0x90, v17
	v_lshlrev_b32_e32 v8, 5, v162
	v_or3_b32 v140, v8, s6, v17
	s_lshl_b32 s6, s12, 14
	v_lshlrev_b32_e32 v8, 13, v160
	v_add3_u32 v8, v8, s6, v140
	v_ashrrev_i32_e32 v9, 31, v8
	v_lshlrev_b64 v[8:9], 7, v[8:9]
	v_lshl_add_u64 v[8:9], s[38:39], 0, v[8:9]
	v_lshl_add_u64 v[8:9], v[8:9], 0, v[188:189]
	global_load_dwordx4 v[112:115], v[8:9], off
	global_load_dwordx4 v[116:119], v[8:9], off offset:32
	global_load_dwordx4 v[124:127], v[8:9], off offset:64
	global_load_dwordx4 v[120:123], v[8:9], off offset:96
	v_readlane_b32 s6, v248, 38
	v_readlane_b32 s7, v248, 39
	v_lshl_add_u32 v14, s12, 1, v160
	v_ashrrev_i32_e32 v15, 31, v14
	v_lshl_add_u64 v[14:15], v[14:15], 2, s[6:7]
	global_load_dword v14, v[14:15], off
	s_lshl_b32 s6, s12, 21
	s_add_u32 s6, s40, s6
	v_lshlrev_b32_e32 v10, 3, v161
	v_ashrrev_i32_e32 v11, 31, v10
	s_addc_u32 s7, s41, 0
	v_lshlrev_b64 v[32:33], 1, v[10:11]
	v_lshl_add_u64 v[22:23], s[6:7], 0, v[32:33]
	s_mul_i32 s6, s12, 0x204000
	s_add_u32 s6, s42, s6
	v_and_b32_e32 v11, 56, v10
	s_addc_u32 s7, s43, 0
	v_lshlrev_b32_e32 v142, 1, v11
	v_add_u32_e32 v11, 0x200, v161
	v_lshl_add_u64 v[12:13], s[6:7], 0, v[142:143]
	v_ashrrev_i32_e32 v25, 3, v11
	v_mad_i64_i32 v[34:35], s[6:7], v24, s14, 0
	v_mad_i64_i32 v[36:37], s[6:7], v25, s14, 0
	v_mad_i64_i32 v[18:19], s[6:7], v25, s14, v[12:13]
	v_mad_i64_i32 v[20:21], s[6:7], v24, s14, v[12:13]
	s_mov_b32 s6, 0x100000
	s_nop 0
	v_add_co_u32_e32 v8, vcc, s6, v22
	v_and_b32_e32 v26, 48, v10
	v_lshlrev_b32_e32 v10, 2, v161
	v_addc_co_u32_e32 v9, vcc, 0, v23, vcc
	v_and_b32_e32 v27, 4, v10
	global_load_dwordx4 v[80:83], v[18:19], off
	global_load_dwordx4 v[84:87], v[20:21], off
	s_nop 0
	global_load_dwordx4 v[88:91], v[8:9], off
	s_nop 0
	global_load_dwordx4 v[92:95], v[22:23], off
	v_mov_b32_e32 v38, v167
	v_mov_b32_e32 v39, v167
	v_mov_b32_e32 v40, v167
	v_mov_b32_e32 v41, v167
	v_mov_b32_e32 v42, v167
	v_mov_b32_e32 v43, v167
	v_mov_b32_e32 v44, v167
	v_mov_b32_e32 v45, v167
	v_mov_b32_e32 v46, v167
	v_mov_b32_e32 v47, v167
	v_mov_b32_e32 v48, 0
	v_mov_b32_e32 v49, v167
	v_mov_b32_e32 v50, v167
	v_mov_b32_e32 v51, v167
	v_mov_b32_e32 v52, v167
	v_mov_b32_e32 v53, v167
	v_mov_b32_e32 v54, v167
	v_mov_b32_e32 v55, v167
	v_mov_b32_e32 v56, v167
	v_mov_b32_e32 v57, v167
	v_mov_b32_e32 v58, v167
	v_mov_b32_e32 v59, v167
	v_mov_b32_e32 v60, v167
	v_mov_b32_e32 v61, v167
	v_mov_b32_e32 v62, v167
	v_mov_b32_e32 v63, v167
	v_mov_b32_e32 v64, 0
	v_mov_b32_e32 v65, v167
	v_mov_b32_e32 v66, v167
	v_mov_b32_e32 v67, v167
	v_mov_b32_e32 v68, v167
	v_mov_b32_e32 v69, v167
	v_mov_b32_e32 v70, v167
	v_mov_b32_e32 v71, v167
	v_mov_b32_e32 v72, v167
	v_mov_b32_e32 v73, v167
	v_mov_b32_e32 v74, v167
	v_mov_b32_e32 v75, v167
	v_mov_b32_e32 v76, v167
	v_mov_b32_e32 v77, v167
	v_mov_b32_e32 v78, v167
	v_mov_b32_e32 v79, v167
	v_readlane_b32 s74, v248, 32
	v_readlane_b32 s75, v248, 33
	s_waitcnt vmcnt(11)
	v_mul_f32_e32 v6, v4, v5
	ds_bpermute_b32 v6, v158, v6
	s_waitcnt vmcnt(9)
	v_mul_f32_e32 v1, v2, v0
	ds_bpermute_b32 v1, v158, v1
	s_waitcnt lgkmcnt(1)
	v_fmac_f32_e32 v6, v4, v5
	s_waitcnt lgkmcnt(0)
	v_fmac_f32_e32 v1, v2, v0
	v_xor_b32_e32 v0, 16, v215
	v_cmp_lt_i32_e32 vcc, v0, v3
	s_nop 1
	v_cndmask_b32_e32 v0, v215, v0, vcc
	v_lshlrev_b32_e32 v0, 2, v0
	ds_bpermute_b32 v2, v0, v6
	ds_bpermute_b32 v0, v0, v1
	s_waitcnt lgkmcnt(1)
	v_add_f32_e32 v2, v6, v2
	s_waitcnt lgkmcnt(0)
	v_add_f32_e32 v0, v1, v0
	v_xor_b32_e32 v1, 8, v215
	v_cmp_lt_i32_e32 vcc, v1, v3
	s_nop 1
	v_cndmask_b32_e32 v1, v215, v1, vcc
	v_lshlrev_b32_e32 v1, 2, v1
	ds_bpermute_b32 v4, v1, v2
	ds_bpermute_b32 v1, v1, v0
	s_waitcnt lgkmcnt(1)
	v_add_f32_e32 v2, v2, v4
	s_waitcnt lgkmcnt(0)
	v_add_f32_e32 v0, v0, v1
	v_xor_b32_e32 v1, 4, v215
	v_cmp_lt_i32_e32 vcc, v1, v3
	s_nop 1
	v_cndmask_b32_e32 v1, v215, v1, vcc
	v_lshlrev_b32_e32 v1, 2, v1
	ds_bpermute_b32 v4, v1, v2
	ds_bpermute_b32 v1, v1, v0
	s_waitcnt lgkmcnt(1)
	v_add_f32_e32 v2, v2, v4
	s_waitcnt lgkmcnt(0)
	v_add_f32_e32 v0, v0, v1
	v_xor_b32_e32 v1, 2, v215
	v_cmp_lt_i32_e32 vcc, v1, v3
	s_nop 1
	v_cndmask_b32_e32 v1, v215, v1, vcc
	v_lshlrev_b32_e32 v1, 2, v1
	ds_bpermute_b32 v4, v1, v2
	ds_bpermute_b32 v1, v1, v0
	s_waitcnt lgkmcnt(1)
	v_add_f32_e32 v163, v2, v4
	s_waitcnt lgkmcnt(0)
	v_add_f32_e32 v165, v0, v1
	v_xor_b32_e32 v0, 1, v215
	v_cmp_lt_i32_e32 vcc, v0, v3
	s_nop 1
	v_cndmask_b32_e32 v0, v215, v0, vcc
	v_lshlrev_b32_e32 v0, 2, v0
	ds_bpermute_b32 v164, v0, v163
	ds_bpermute_b32 v166, v0, v165
	s_waitcnt vmcnt(8)
; DI float bf2f(unsigned v) { return __uint_as_float(v << 16); }
; DI f32x16 zero16() { f32x16 z; for (int i = 0; i < 16; ++i) z[i] = 0.f; return z; }
; DI void attn_item(const P& p, int l, int item, char* smem) {
;     ...
;     float q2 = 0.f;
; #pragma unroll
;     for (int ks = 0; ks < 4; ++ks) {
;       qf[ks] = *(const bf16x8*)(p.Qb + ((size_t)((bh * 2 + c) * SEQ + tq)) * 64 + 16 * ks + 8 * g);
; #pragma unroll
;       for (int j = 0; j < 8; ++j) { const float v = bf2f((unsigned)(u16)qf[ks][j]); q2 += v * v; }
;     }
;     q2 += __shfl_xor(q2, 32);
;     const float k2 = __uint_as_float(p.kmax[bh * 2 + c]);
;     negm = -(sqrtf(q2 * k2) * 1.01f + 1e-3f);
;   }
;   f32x16 O[4];
; #pragma unroll
;   for (int eb = 0; eb < 4; ++eb) O[eb] = zero16();
;   float ls = 0.f;
;   u32x4 kreg[2], vreg[2];
;   const u16* kbase = p.Kb + (size_t)(bh * 2) * SEQ * 64;
;   const u16* vbase = p.VT + (size_t)(bh * 128) * VTP;
; #pragma unroll
;   for (int i = 0; i < 2; ++i) kreg[i] = *(const u32x4*)(kbase + ((size_t)i * SEQ) * 64 + tid * 8);
; #pragma unroll
;   for (int i = 0; i < 2; ++i) {
;     const int cid = tid + NT * i;
;     const int e = cid >> 3, kc = cid & 7;
;     vreg[i] = *(const u32x4*)(vbase + (size_t)e * VTP + kc * 8);
;   }
;   for (int kt = -1; kt < 128; ++kt) {
;     if (kt + 1 < 128) {
;       u16* Kd = Ks + ((kt + 1) & 1) * (256 * 72);
;       u16* Vd = Kd + 2 * 64 * 72;
; #pragma unroll
;       for (int i = 0; i < 2; ++i) {
;         const int row = tid >> 3, kc = tid & 7;
;         *(u32x4*)(Kd + (i * 64 + row) * 72 + kc * 8) = kreg[i];
;       }
; #pragma unroll
;       for (int i = 0; i < 2; ++i) {
;         const int cid = tid + NT * i;
;         const int e = cid >> 3, kc = cid & 7;
;         uint2 w0; w0.x = vreg[i][0]; w0.y = vreg[i][1];
;         uint2 w1; w1.x = vreg[i][2]; w1.y = vreg[i][3];
;         u16* vd = Vd + e * 72 + (kc >> 1) * 16 + (kc & 1) * 4;
;         *(uint2*)vd = w0;
;         *(uint2*)(vd + 8) = w1;
;       }
;     }
;     if (kt + 2 < 128) {
;       const int kn = kt + 2;
; #pragma unroll
;       for (int i = 0; i < 2; ++i) kreg[i] = *(const u32x4*)(kbase + ((size_t)i * SEQ + kn * 64) * 64 + tid * 8);
; #pragma unroll
;       for (int i = 0; i < 2; ++i) {
;         const int cid = tid + NT * i;
;         const int e = cid >> 3, kc = cid & 7;
;         vreg[i] = *(const u32x4*)(vbase + (size_t)e * VTP + kn * 64 + kc * 8);
;       }
	v_and_b32_e32 v3, 0xffff0000, v112
	v_lshlrev_b32_e32 v2, 16, v112
	v_mul_f32_e32 v3, v3, v3
	v_fmac_f32_e32 v3, v2, v2
	v_lshlrev_b32_e32 v2, 16, v113
	v_fmac_f32_e32 v3, v2, v2
	v_and_b32_e32 v2, 0xffff0000, v113
	v_fmac_f32_e32 v3, v2, v2
	v_lshlrev_b32_e32 v2, 16, v114
	v_fmac_f32_e32 v3, v2, v2
	v_and_b32_e32 v2, 0xffff0000, v114
	v_fmac_f32_e32 v3, v2, v2
	v_lshlrev_b32_e32 v2, 16, v115
	v_fmac_f32_e32 v3, v2, v2
	v_and_b32_e32 v2, 0xffff0000, v115
	v_fmac_f32_e32 v3, v2, v2
	s_waitcnt vmcnt(7)
	v_lshlrev_b32_e32 v2, 16, v116
	v_fmac_f32_e32 v3, v2, v2
	v_and_b32_e32 v2, 0xffff0000, v116
	v_fmac_f32_e32 v3, v2, v2
	v_lshlrev_b32_e32 v2, 16, v117
	v_fmac_f32_e32 v3, v2, v2
	v_and_b32_e32 v2, 0xffff0000, v117
	v_fmac_f32_e32 v3, v2, v2
	v_lshlrev_b32_e32 v2, 16, v118
	v_fmac_f32_e32 v3, v2, v2
	v_and_b32_e32 v2, 0xffff0000, v118
	v_fmac_f32_e32 v3, v2, v2
	v_lshlrev_b32_e32 v2, 16, v119
	v_fmac_f32_e32 v3, v2, v2
	v_and_b32_e32 v2, 0xffff0000, v119
	v_fmac_f32_e32 v3, v2, v2
	s_waitcnt vmcnt(6)
	v_lshlrev_b32_e32 v2, 16, v124
	v_fmac_f32_e32 v3, v2, v2
	v_and_b32_e32 v2, 0xffff0000, v124
	v_fmac_f32_e32 v3, v2, v2
	v_lshlrev_b32_e32 v2, 16, v125
	v_fmac_f32_e32 v3, v2, v2
	v_and_b32_e32 v2, 0xffff0000, v125
	v_fmac_f32_e32 v3, v2, v2
	v_lshlrev_b32_e32 v2, 16, v126
	v_fmac_f32_e32 v3, v2, v2
	v_and_b32_e32 v2, 0xffff0000, v126
	v_fmac_f32_e32 v3, v2, v2
	v_lshlrev_b32_e32 v2, 16, v127
	v_fmac_f32_e32 v3, v2, v2
	v_and_b32_e32 v2, 0xffff0000, v127
	v_fmac_f32_e32 v3, v2, v2
	s_waitcnt vmcnt(5)
	v_lshlrev_b32_e32 v0, 16, v120
	v_fmac_f32_e32 v3, v0, v0
	v_and_b32_e32 v0, 0xffff0000, v120
	v_fmac_f32_e32 v3, v0, v0
	v_and_b32_e32 v1, 0xffff0000, v121
	v_lshlrev_b32_e32 v0, 16, v121
	v_pk_mul_f32 v[0:1], v[0:1], v[0:1]
	s_nop 0
	v_add_f32_e32 v0, v0, v3
	v_add_f32_e32 v2, v1, v0
	v_and_b32_e32 v1, 0xffff0000, v122
	v_lshlrev_b32_e32 v0, 16, v122
	v_pk_mul_f32 v[0:1], v[0:1], v[0:1]
	s_nop 0
	v_add_f32_e32 v0, v0, v2
	v_add_f32_e32 v2, v1, v0
	v_and_b32_e32 v1, 0xffff0000, v123
	v_lshlrev_b32_e32 v0, 16, v123
	v_pk_mul_f32 v[0:1], v[0:1], v[0:1]
	s_nop 0
	v_add_f32_e32 v0, v0, v2
	v_add_f32_e32 v0, v1, v0
	ds_bpermute_b32 v1, v158, v0
	s_waitcnt lgkmcnt(0)
	v_add_f32_e32 v2, v0, v1
	s_mov_b32 s6, 0xf800000
	s_waitcnt vmcnt(4)
	v_mul_f32_e32 v0, v14, v2
	v_cmp_gt_f32_e32 vcc, s6, v0
	v_mul_f32_e32 v1, 0x4f800000, v0
	s_nop 0
	v_cndmask_b32_e32 v0, v0, v1, vcc
	v_sqrt_f32_e32 v1, v0
	s_nop 0
	v_add_u32_e32 v2, -1, v1
	v_fma_f32 v3, -v2, v1, v0
	v_cmp_ge_f32_e64 s[6:7], 0, v3
	v_add_u32_e32 v3, 1, v1
	s_nop 0
	v_cndmask_b32_e64 v2, v1, v2, s[6:7]
	v_fma_f32 v1, -v3, v1, v0
	v_cmp_lt_f32_e64 s[6:7], 0, v1
	s_nop 1
	v_cndmask_b32_e64 v1, v2, v3, s[6:7]
	v_mul_f32_e32 v2, 0x37800000, v1
	v_cndmask_b32_e32 v1, v1, v2, vcc
	v_cmp_class_f32_e32 vcc, v0, v208
	s_nop 0
	s_nop 0
	v_cndmask_b32_e32 v0, v1, v0, vcc
	v_fmamk_f32 v2, v0, 0x3f8147ae, v209
	v_xor_b32_e32 v16, 0x80000000, v2
	v_add_u32_e32 v28, 0, v142
	v_add_u32_e32 v168, v28, v170
	v_lshlrev_b32_e32 v171, 1, v26
	v_lshlrev_b32_e32 v172, 1, v27
	s_waitcnt vmcnt(0)
	ds_write_b128 v168, v[92:95]
	ds_write_b128 v168, v[88:91] offset:9216
	v_add3_u32 v8, 0, v171, v172
	v_add_u32_e32 v169, v8, v170
	v_mul_lo_u32 v173, v25, s94
	v_add_u32_e32 v9, 0x4800, v169
	v_add_u32_e32 v143, v8, v173
	ds_write2_b64 v9, v[84:85], v[86:87] offset1:2
	v_add_u32_e32 v4, 0x4800, v143
	ds_write2_b64 v4, v[80:81], v[82:83] offset1:2
	v_add_co_u32_e32 v0, vcc, s65, v22
	s_mov_b32 s6, 0x102000
	s_nop 0
	v_addc_co_u32_e32 v1, vcc, 0, v23, vcc
	global_load_dwordx4 v[228:231], v[0:1], off
	v_add_co_u32_e32 v0, vcc, s6, v22
	v_lshlrev_b32_e32 v2, 4, v161
	s_nop 0
	v_addc_co_u32_e32 v1, vcc, 0, v23, vcc
	global_load_dwordx4 v[232:235], v[0:1], off
	global_load_dwordx4 v[236:239], v[20:21], off offset:128
	global_load_dwordx4 v[240:243], v[18:19], off offset:128
	v_lshl_or_b32 v0, v160, 6, v17
	v_mul_lo_u32 v175, v0, s94
	v_mad_u64_u32 v[0:1], s[6:7], s13, v219, v[36:37]
	v_and_b32_e32 v2, 0x70, v2
	v_or_b32_e32 v0, v0, v2
	v_lshl_add_u64 v[144:145], s[70:71], 0, v[0:1]
	v_mad_u64_u32 v[0:1], s[6:7], s13, v219, v[34:35]
	v_readlane_b32 s6, v248, 42
	s_add_u32 s6, s6, s11
	v_readlane_b32 s7, v248, 43
	v_or_b32_e32 v0, v0, v2
	s_addc_u32 s7, s7, 0
	v_mov_b32_e32 v17, v16
	v_mov_b32_e32 v18, v16
	v_mov_b32_e32 v19, v16
	v_mov_b32_e32 v20, v16
	v_mov_b32_e32 v21, v16
	v_mov_b32_e32 v22, v16
	v_mov_b32_e32 v23, v16
	v_mov_b32_e32 v24, v16
	v_mov_b32_e32 v25, v16
	v_mov_b32_e32 v26, v16
	v_mov_b32_e32 v27, v16
	v_mov_b32_e32 v28, v16
	v_mov_b32_e32 v29, v16
	v_mov_b32_e32 v30, v16
	v_mov_b32_e32 v31, v16
	v_lshl_add_u64 v[146:147], s[70:71], 0, v[0:1]
	v_lshl_add_u64 v[148:149], s[6:7], 0, v[32:33]
	v_mov_b32_e32 v0, 0
	v_mov_b32_e32 v1, v167
	v_mov_b32_e32 v2, v167
	v_mov_b32_e32 v3, v167
	v_mov_b32_e32 v4, v167
	v_mov_b32_e32 v5, v167
	v_mov_b32_e32 v6, v167
	v_mov_b32_e32 v7, v167
	v_mov_b32_e32 v8, v167
	v_mov_b32_e32 v9, v167
	v_mov_b32_e32 v10, v167
	v_mov_b32_e32 v11, v167
	v_mov_b32_e32 v12, v167
	v_mov_b32_e32 v13, v167
	v_mov_b32_e32 v14, v167
	v_mov_b32_e32 v15, v167
	v_mov_b32_e32 v32, 0
	v_mov_b32_e32 v33, v167
	v_mov_b32_e32 v34, v167
	v_mov_b32_e32 v35, v167
	v_mov_b32_e32 v36, v167
	v_mov_b32_e32 v37, v167
	s_waitcnt lgkmcnt(0)
	s_barrier
; #define MFMA(a, b, c) __builtin_amdgcn_mfma_f32_32x32x16_bf16((a), (b), (c), 0, 0, 0)
; DI void attn_item(const P& p, int l, int item, char* smem) {
;     ...
;     if (kt >= 0) {
;       const u16* Kc = Ks + (kt & 1) * (256 * 72);
;       const u16* Vc = Kc + 2 * 64 * 72;
;       bf16x8 kf[8];
; #pragma unroll
;       for (int i = 0; i < 8; ++i)
;         kf[i] = *(const bf16x8*)(Kc + (c * 64 + 32 * (i & 1) + li) * 72 + 16 * (i >> 1) + 8 * g);
;       u32x4 vf[16];
; #pragma unroll
;       for (int i = 0; i < 16; ++i) {
;         const int eb = i & 3, s = (i >> 2) & 1, kb = i >> 3;
;         vf[i] = *(const u32x4*)(Vc + (32 * eb + li) * 72 + 32 * kb + 16 * s + 8 * g);
;       }
;       f32x16 S[2];
; #pragma unroll
;       for (int kb = 0; kb < 2; ++kb)
; #pragma unroll
;         for (int r = 0; r < 16; ++r) S[kb][r] = negm;
; #pragma unroll
;       for (int i = 0; i < 8; ++i) S[i & 1] = MFMA(kf[i], qf[i >> 1], S[i & 1]);
;       u32x4 pk[4];
;       float sum = 0.f;
; #pragma unroll
;       for (int ch = 0; ch < 4; ++ch) {
;         const int kb = ch >> 1, s = ch & 1;
; #pragma unroll
;         for (int j2 = 0; j2 < 4; ++j2) {
;           const float p0 = __builtin_amdgcn_exp2f(S[kb][8 * s + 2 * j2]);
;           const float p1 = __builtin_amdgcn_exp2f(S[kb][8 * s + 2 * j2 + 1]);
;           sum += p0 + p1;
;           pk[ch][j2] = pack2(p0, p1);
;         }
;       }
;       ls += sum;
	v_add_u32_e32 v150, v175, v188
	v_add_u32_e32 v151, v174, v188
	s_mov_b32 s10, 0xfff00000
	v_add_co_u32_e32 v156, vcc, s10, v148
	v_add_u32_e32 v151, 0x4800, v151
	s_mov_b64 s[14:15], 0x2000
	v_addc_co_u32_e32 v157, vcc, -1, v149, vcc
	v_mov_b32_e32 v190, 0
	v_mov_b32_e32 v191, 0
	v_mov_b32_e32 v196, 0
	s_movk_i32 s10, 63
	ds_read_b128 v[128:131], v150 offset:0
	ds_read_b128 v[132:135], v150 offset:32
	ds_read_b128 v[136:139], v150 offset:64
	ds_read_b128 v[152:155], v150 offset:96
	ds_read_b128 v[224:227], v150 offset:4608
	ds_read_b128 v[244:247], v150 offset:4640
	s_waitcnt lgkmcnt(4)
	v_mfma_f32_32x32x16_bf16 v[96:111], v[128:131], v[112:115], v[16:31]
	ds_read_b128 v[128:131], v150 offset:4672
	v_mfma_f32_32x32x16_bf16 v[96:111], v[132:135], v[116:119], v[96:111]
	ds_read_b128 v[132:135], v150 offset:4704
	s_waitcnt lgkmcnt(4)
	v_mfma_f32_32x32x16_bf16 v[96:111], v[136:139], v[124:127], v[96:111]
	ds_read_b128 v[136:139], v151 offset:0
	v_mfma_f32_32x32x16_bf16 v[96:111], v[152:155], v[120:123], v[96:111]
	ds_read_b128 v[152:155], v151 offset:4608
	s_waitcnt lgkmcnt(4)
	v_mfma_f32_32x32x16_bf16 v[80:95], v[224:227], v[112:115], v[16:31]
	ds_read_b128 v[224:227], v151 offset:9216
	v_mfma_f32_32x32x16_bf16 v[80:95], v[244:247], v[116:119], v[80:95]
	ds_read_b128 v[244:247], v151 offset:13824
	s_nop 6
	v_exp_f32_e32 v96, v96
	v_exp_f32_e32 v97, v97
	s_waitcnt lgkmcnt(4)
	v_mfma_f32_32x32x16_bf16 v[80:95], v[128:131], v[124:127], v[80:95]
	ds_read_b128 v[128:131], v151 offset:32
	v_exp_f32_e32 v98, v98
	v_exp_f32_e32 v99, v99
	v_exp_f32_e32 v100, v100
	v_mfma_f32_32x32x16_bf16 v[80:95], v[132:135], v[120:123], v[80:95]
	ds_read_b128 v[132:135], v151 offset:4640
	v_exp_f32_e32 v101, v101
	v_exp_f32_e32 v102, v102
	v_exp_f32_e32 v103, v103
	v_add_f32_e32 v167, v167, v96
	v_add_f32_e32 v190, v190, v97
	v_add_f32_e32 v191, v191, v98
	v_cvt_pk_bf16_f32 v176, v96, v97
	v_cvt_pk_bf16_f32 v177, v98, v99
	v_cvt_pk_bf16_f32 v178, v100, v101
	v_cvt_pk_bf16_f32 v179, v102, v103
	v_add_f32_e32 v196, v196, v99
	v_add_f32_e32 v167, v167, v100
	v_add_f32_e32 v190, v190, v101
	v_add_f32_e32 v191, v191, v102
	v_add_f32_e32 v196, v196, v103
